# v16 + loop-invariant norm-gain loads hoisted out of three rw_phase row loops
# speedup vs baseline: 1.0186x; 1.0006x over previous
; #define KP(f) ((decltype(Params::f))(char*)(gchar_t*)(char*)karg((int)offsetof(Params, f)))
; DI int otid() { int t = threadIdx.x; asm volatile("" : "+v"(t)); return t; }
; DI void rw_phase(const float* x, bf16_t* hb, const bf16_t* y, const float* gpost, float* rh, float* fout, bool y_unscaled) {
;   const int tid_ = otid(), wid = tid_ >> 6, lane = tid_ & 63;
;   for (int row = blockIdx.x * 8 + wid; row < T_; row += gridDim.x * 8) {
; __global__ void __launch_bounds__(512, 2) mega(Params p) {
;     ...
;       } else if (kind == 1) {
;         if (s == 0) { is_gemm = true; g.A = bU; g.Bt = W + W_IN; g.N = 2048; g.K = 1024; g.epi = EPI_GLU; g.o0 = bA; g.bias = KP(conv_b_in); g.rowscale = rh; }
;         else if (s == 1) conv_phase(bA, bB, lds);
;         else if (s == 2) { is_gemm = true; g.A = bB; g.Bt = W + W_OUT; g.N = 1024; g.K = 1024; g.epi = EPI_PLAIN; g.o0 = bC; g.bias = KP(conv_b_out); }
;         else rw_phase(nullptr, bU, bC, gl + 1024, rh, nullptr, false);
.LBB0_428:
	s_andn2_b64 vcc, exec, s[0:1]
	s_mov_b64 s[0:1], 0
	s_cbranch_vccnz .LBB0_436
	s_cmp_lg_u32 s4, 3
	s_cselect_b32 s5, s4, 0
	s_add_u32 s0, s20, 0xa000000
	s_addc_u32 s1, s21, 0
	v_writelane_b32 v255, s0, 39
	s_mov_b64 s[48:49], -1
	s_mov_b64 s[86:87], 0
	v_writelane_b32 v255, s1, 40
	s_add_u32 s0, s20, 0x1e000000
	s_addc_u32 s1, s21, 0
	v_writelane_b32 v255, s0, 41
	s_mov_b64 s[26:27], 0
	s_nop 0
	v_writelane_b32 v255, s1, 42
	s_add_u32 s0, s20, 0x1f400000
	s_addc_u32 s1, s21, 0
	v_writelane_b32 v255, s0, 43
	s_cmp_lt_i32 s5, 1
	s_nop 0
	v_writelane_b32 v255, s1, 44
	s_mov_b64 s[0:1], 0
	s_cbranch_scc1 .LBB0_721
	s_mov_b64 s[26:27], -1
	s_mov_b64 s[48:49], 0
	s_cmp_eq_u32 s5, 1
	s_cbranch_scc0 .LBB0_721
	s_mov_b64 s[22:23], 0
	s_cmp_lt_i32 s91, 1
	s_cbranch_scc1 .LBB0_719
	s_cmp_gt_i32 s91, 1
	v_readlane_b32 s24, v255, 7
	s_mov_b32 s63, 0x8000
	s_movk_i32 s44, 0x7fff
	s_movk_i32 s80, 0x2000
	s_cbranch_scc0 .LBB0_511
	s_cmp_lg_u32 s91, 2
	s_mov_b64 s[0:1], -1
	s_cbranch_scc0 .LBB0_646
	s_waitcnt lgkmcnt(0)
	v_mov_b32_e32 v1, v159
	v_readlane_b32 s0, v254, 4
	v_ashrrev_i32_e32 v0, 6, v1
	s_nop 0
	v_add_u32_e32 v0, s0, v0
	v_cmp_gt_i32_e32 vcc, s63, v0
	s_and_saveexec_b64 s[0:1], vcc
	s_cbranch_execz .LBB0_645
	v_and_b32_e32 v1, 63, v1
	v_readlane_b32 s26, v255, 35
	v_lshlrev_b32_e32 v148, 4, v1
	v_readlane_b32 s27, v255, 36
	v_cmp_lt_i32_e64 s[42:43], v209, v208
	v_lshl_add_u64 v[2:3], s[30:31], 0, v[148:149]
	v_lshl_add_u64 v[4:5], s[26:27], 0, v[148:149]
	v_lshlrev_b32_e32 v148, 5, v1
	v_cmp_eq_u32_e32 vcc, 0, v1
	v_cndmask_b32_e64 v1, v206, v209, s[42:43]
	v_cmp_lt_i32_e64 s[42:43], v210, v208
	v_lshlrev_b32_e32 v10, 2, v1
	v_readlane_b32 s26, v255, 37
	v_cndmask_b32_e64 v1, v206, v210, s[42:43]
	v_cmp_lt_i32_e64 s[42:43], v211, v208
	v_lshlrev_b32_e32 v11, 2, v1
	v_readlane_b32 s27, v255, 38
	v_cndmask_b32_e64 v1, v206, v211, s[42:43]
	v_lshlrev_b32_e32 v12, 2, v1
	v_xor_b32_e32 v1, 8, v206
	v_cmp_lt_i32_e64 s[42:43], v1, v208
	v_lshl_add_u64 v[6:7], s[26:27], 0, v[148:149]
	s_mov_b64 s[26:27], 0x1000
	v_cndmask_b32_e64 v1, v206, v1, s[42:43]
	v_lshlrev_b32_e32 v13, 2, v1
	v_xor_b32_e32 v1, 16, v206
	v_cmp_lt_i32_e64 s[42:43], v1, v208
	v_lshl_add_u64 v[6:7], v[6:7], 0, s[26:27]
	s_mov_b64 s[26:27], 0
	v_cndmask_b32_e64 v1, v206, v1, s[42:43]
	v_cmp_lt_i32_e64 s[42:43], v214, v208
	v_lshlrev_b32_e32 v14, 2, v1
	s_nop 0
	v_cndmask_b32_e64 v1, v206, v214, s[42:43]
	v_lshlrev_b32_e32 v15, 2, v1
	global_load_dwordx4 v[76:79], v[6:7], off offset:16
	global_load_dwordx4 v[80:83], v[6:7], off
	global_load_dwordx4 v[84:87], v[6:7], off offset:2064
	global_load_dwordx4 v[88:91], v[6:7], off offset:2048
	s_branch .LBB0_488

; DI float bflo(unsigned w) { return __uint_as_float(w << 16); }
; DI float bfhi(unsigned w) { return __uint_as_float(w & 0xffff0000u); }
; DI void rw_phase(const float* x, bf16_t* hb, const bf16_t* y, const float* gpost, float* rh, float* fout, bool y_unscaled) {
;     ...
;     if (y) {
;       float yv[16]; float ss = 0.f;
; #pragma unroll
;       for (int c = 0; c < 2; ++c) {
;         const u32x4 w = gld<u32x4>(y + (size_t)row * 1024 + 512 * c + 8 * lane);
;         yv[8 * c + 0] = bflo(w.x); yv[8 * c + 1] = bfhi(w.x); yv[8 * c + 2] = bflo(w.y); yv[8 * c + 3] = bfhi(w.y);
;         yv[8 * c + 4] = bflo(w.z); yv[8 * c + 5] = bfhi(w.z); yv[8 * c + 6] = bflo(w.w); yv[8 * c + 7] = bfhi(w.w);
;       }
; #pragma unroll
;       for (int i = 0; i < 16; ++i) ss += yv[i] * yv[i];
;       ss = wave_sum(ss);
;       float epsn = EPS;
;       if (y_unscaled) { const float r = gld<float>(rh + row), r2 = r * r; epsn = EPS / (r2 * r2); }
;       const float ry = rsqrtf(ss * (1.0f / 1024.0f) + epsn);
; #pragma unroll
;       for (int c = 0; c < 2; ++c) {
;         const f32x4 g0 = gld<f32x4>(gpost + 512 * c + 8 * lane), g1 = gld<f32x4>(gpost + 512 * c + 8 * lane + 4);
; #pragma unroll
;         for (int i = 0; i < 4; ++i) { hv[8 * c + i] += yv[8 * c + i] * ry * g0[i]; hv[8 * c + 4 + i] += yv[8 * c + 4 + i] * ry * g1[i]; }
;       }
;     }
;     if (fout) {
;       float* op = fout + (size_t)row * 1024;
; #pragma unroll
;       for (int c = 0; c < 2; ++c) {
;         gst<f32x4>(op + 512 * c + 8 * lane, (f32x4){hv[8 * c], hv[8 * c + 1], hv[8 * c + 2], hv[8 * c + 3]});
;         gst<f32x4>(op + 512 * c + 8 * lane + 4, (f32x4){hv[8 * c + 4], hv[8 * c + 5], hv[8 * c + 6], hv[8 * c + 7]});
;       }
;     } else {
;       float s2 = 0.f;
; #pragma unroll
;       for (int c = 0; c < 2; ++c) {
;         u32x4 w;
;         w.x = pk(hv[8 * c + 0], hv[8 * c + 1]); w.y = pk(hv[8 * c + 2], hv[8 * c + 3]); w.z = pk(hv[8 * c + 4], hv[8 * c + 5]); w.w = pk(hv[8 * c + 6], hv[8 * c + 7]);
;         gst<u32x4>(hb + (size_t)row * 1024 + 512 * c + 8 * lane, w);
;         s2 += bflo(w.x) * bflo(w.x) + bfhi(w.x) * bfhi(w.x) + bflo(w.y) * bflo(w.y) + bfhi(w.y) * bfhi(w.y) +
;               bflo(w.z) * bflo(w.z) + bfhi(w.z) * bfhi(w.z) + bflo(w.w) * bflo(w.w) + bfhi(w.w) * bfhi(w.w);
;       }
;       s2 = wave_sum(s2);
;       if (lane == 0) gst<float>(rh + row, rsqrtf(s2 * (1.0f / 1024.0f) + EPS));
.LBB0_488:
	v_ashrrev_i32_e32 v1, 31, v0
	v_lshlrev_b64 v[8:9], 11, v[0:1]
	v_lshl_add_u64 v[20:21], v[4:5], 0, v[8:9]
	s_waitcnt lgkmcnt(0)
	global_load_dwordx4 v[16:19], v[20:21], off offset:1024
	s_nop 0
	global_load_dwordx4 v[20:23], v[20:21], off
	v_lshl_add_u64 v[8:9], v[2:3], 0, v[8:9]
	global_load_dwordx4 v[24:27], v[8:9], off offset:1024
	global_load_dwordx4 v[28:31], v[8:9], off
	s_waitcnt vmcnt(0)
	v_lshlrev_b32_e32 v48, 16, v19
	v_lshlrev_b32_e32 v56, 16, v20
	v_and_b32_e32 v57, 0xffff0000, v20
	v_and_b32_e32 v49, 0xffff0000, v19
	v_lshlrev_b32_e32 v50, 16, v18
	v_and_b32_e32 v51, 0xffff0000, v18
	v_lshlrev_b32_e32 v18, 16, v17
	v_and_b32_e32 v19, 0xffff0000, v17
	v_lshlrev_b32_e32 v52, 16, v16
	v_and_b32_e32 v53, 0xffff0000, v16
	v_lshlrev_b32_e32 v16, 16, v23
	v_and_b32_e32 v17, 0xffff0000, v23
	v_lshlrev_b32_e32 v54, 16, v22
	v_and_b32_e32 v55, 0xffff0000, v22
	v_lshlrev_b32_e32 v22, 16, v21
	v_and_b32_e32 v23, 0xffff0000, v21
	v_pk_mul_f32 v[70:71], v[56:57], v[56:57]
	v_pk_mul_f32 v[68:69], v[22:23], v[22:23]
	v_add_f32_e32 v70, v70, v71
	v_add_f32_e32 v68, v68, v70
	v_pk_mul_f32 v[66:67], v[54:55], v[54:55]
	v_add_f32_e32 v68, v69, v68
	v_add_f32_e32 v66, v66, v68
	v_pk_mul_f32 v[64:65], v[16:17], v[16:17]
	v_add_f32_e32 v66, v67, v66
	v_add_f32_e32 v64, v64, v66
	v_pk_mul_f32 v[62:63], v[52:53], v[52:53]
	v_add_f32_e32 v64, v65, v64
	v_add_f32_e32 v62, v62, v64
	v_pk_mul_f32 v[60:61], v[18:19], v[18:19]
	v_add_f32_e32 v62, v63, v62
	v_add_f32_e32 v60, v60, v62
	v_pk_mul_f32 v[58:59], v[50:51], v[50:51]
	v_add_f32_e32 v60, v61, v60
	v_add_f32_e32 v58, v58, v60
	v_pk_mul_f32 v[20:21], v[48:49], v[48:49]
	v_add_f32_e32 v58, v59, v58
	v_add_f32_e32 v20, v20, v58
	v_add_f32_e32 v20, v21, v20
	s_nop 1
	v_mov_b32_dpp v21, v20 quad_perm:[1,0,3,2] row_mask:0xf bank_mask:0xf
	v_and_b32_e32 v59, 0xffff0000, v26
	s_waitcnt lgkmcnt(0)
	v_add_f32_e32 v20, v20, v21
	s_nop 1
	v_mov_b32_dpp v21, v20 quad_perm:[2,3,0,1] row_mask:0xf bank_mask:0xf
	s_waitcnt lgkmcnt(0)
	v_add_f32_e32 v21, v20, v21
	s_nop 1
	v_mov_b32_dpp v58, v21 row_half_mirror row_mask:0xf bank_mask:0xf
	v_lshlrev_b32_e32 v20, 16, v27
	s_waitcnt lgkmcnt(0)
	v_add_f32_e32 v60, v21, v58
	s_nop 1
	v_mov_b32_dpp v61, v60 row_mirror row_mask:0xf bank_mask:0xf
	v_and_b32_e32 v21, 0xffff0000, v27
	v_lshlrev_b32_e32 v58, 16, v26
	v_lshlrev_b32_e32 v26, 16, v25
	v_and_b32_e32 v27, 0xffff0000, v25
	s_waitcnt lgkmcnt(0)
	v_add_f32_e32 v62, v60, v61
	v_mov_b32_e32 v63, v62
	v_mov_b32_e32 v120, v62
	s_nop 1
	v_permlane16_swap_b32_e32 v63, v120
	v_lshlrev_b32_e32 v60, 16, v24
	v_and_b32_e32 v61, 0xffff0000, v24
	v_lshlrev_b32_e32 v24, 16, v31
	v_and_b32_e32 v25, 0xffff0000, v31
	s_waitcnt lgkmcnt(0)
	v_add_f32_e32 v64, v63, v120
	v_mov_b32_e32 v65, v64
	v_mov_b32_e32 v120, v64
	s_nop 1
	v_permlane32_swap_b32_e32 v65, v120
	v_lshlrev_b32_e32 v62, 16, v30
	v_and_b32_e32 v63, 0xffff0000, v30
	v_lshlrev_b32_e32 v30, 16, v29
	s_waitcnt lgkmcnt(0)
	v_add_f32_e32 v31, v65, v120
	v_fmamk_f32 v31, v31, 0x3a800000, v204
	v_mul_f32_e32 v64, 0x4b800000, v31
	v_cmp_gt_f32_e64 s[42:43], s33, v31
	v_and_b32_e32 v65, 0xffff0000, v28
	s_nop 0
	v_cndmask_b32_e64 v31, v31, v64, s[42:43]
	v_rsq_f32_e32 v66, v31
	v_lshlrev_b32_e32 v64, 16, v28
	v_and_b32_e32 v31, 0xffff0000, v29
	v_mul_f32_e32 v28, 0x45800000, v66
	v_cndmask_b32_e64 v28, v66, v28, s[42:43]
	v_pk_mul_f32 v[56:57], v[28:29], v[56:57] op_sel_hi:[0,1]
	v_pk_mul_f32 v[22:23], v[28:29], v[22:23] op_sel_hi:[0,1]
	v_pk_mul_f32 v[16:17], v[28:29], v[16:17] op_sel_hi:[0,1]
	v_pk_mul_f32 v[52:53], v[28:29], v[52:53] op_sel_hi:[0,1]
	v_pk_mul_f32 v[54:55], v[28:29], v[54:55] op_sel_hi:[0,1]
	v_pk_mul_f32 v[18:19], v[28:29], v[18:19] op_sel_hi:[0,1]
	v_pk_fma_f32 v[36:37], v[80:81], v[56:57], v[64:65]
	v_pk_fma_f32 v[22:23], v[82:83], v[22:23], v[30:31]
	v_pk_fma_f32 v[16:17], v[78:79], v[16:17], v[24:25]
	v_pk_fma_f32 v[24:25], v[88:89], v[52:53], v[60:61]
	v_pk_mul_f32 v[50:51], v[28:29], v[50:51] op_sel_hi:[0,1]
	v_pk_mul_f32 v[28:29], v[28:29], v[48:49] op_sel_hi:[0,1]
	v_pk_fma_f32 v[32:33], v[76:77], v[54:55], v[62:63]
	v_pk_fma_f32 v[26:27], v[90:91], v[18:19], v[26:27]
	v_cvt_pk_bf16_f32 v18, v36, v37
	v_cvt_pk_bf16_f32 v19, v22, v23
	v_cvt_pk_bf16_f32 v22, v24, v25
	v_pk_fma_f32 v[28:29], v[86:87], v[28:29], v[20:21]
	v_cvt_pk_bf16_f32 v20, v32, v33
	v_cvt_pk_bf16_f32 v21, v16, v17
	v_and_b32_e32 v17, 0xffff0000, v18
	v_and_b32_e32 v33, 0xffff0000, v22
	v_cvt_pk_bf16_f32 v23, v26, v27
	v_lshlrev_b32_e32 v16, 16, v18
	v_lshlrev_b32_e32 v32, 16, v22
	v_mul_f32_e32 v17, v17, v17
	v_mul_f32_e32 v33, v33, v33
	v_pk_fma_f32 v[30:31], v[84:85], v[50:51], v[58:59]
	v_lshlrev_b32_e32 v26, 16, v19
	v_lshlrev_b32_e32 v34, 16, v23
	v_fmac_f32_e32 v17, v16, v16
	v_fmac_f32_e32 v33, v32, v32
	v_cvt_pk_bf16_f32 v24, v30, v31
	v_and_b32_e32 v27, 0xffff0000, v19
	v_and_b32_e32 v35, 0xffff0000, v23
	v_fmac_f32_e32 v17, v26, v26
	v_fmac_f32_e32 v33, v34, v34
	v_cvt_pk_bf16_f32 v25, v28, v29
	v_lshlrev_b32_e32 v28, 16, v20
	v_lshlrev_b32_e32 v36, 16, v24
	v_fmac_f32_e32 v17, v27, v27
	v_fmac_f32_e32 v33, v35, v35
	v_and_b32_e32 v29, 0xffff0000, v20
	v_and_b32_e32 v37, 0xffff0000, v24
	v_fmac_f32_e32 v17, v28, v28
	v_fmac_f32_e32 v33, v36, v36
	v_lshlrev_b32_e32 v30, 16, v21
	v_lshlrev_b32_e32 v38, 16, v25
	v_fmac_f32_e32 v17, v29, v29
	v_fmac_f32_e32 v33, v37, v37
	v_and_b32_e32 v31, 0xffff0000, v21
	v_and_b32_e32 v39, 0xffff0000, v25
	v_fmac_f32_e32 v17, v30, v30
	v_fmac_f32_e32 v33, v38, v38
	v_fmac_f32_e32 v17, v31, v31
	v_fmac_f32_e32 v33, v39, v39
	v_add_f32_e32 v16, v17, v33
	s_nop 1
	v_mov_b32_dpp v17, v16 quad_perm:[1,0,3,2] row_mask:0xf bank_mask:0xf
	global_store_dwordx4 v[8:9], v[18:21], off
	global_store_dwordx4 v[8:9], v[22:25], off offset:1024
	s_waitcnt lgkmcnt(0)
	v_add_f32_e32 v16, v16, v17
	s_nop 1
	v_mov_b32_dpp v17, v16 quad_perm:[2,3,0,1] row_mask:0xf bank_mask:0xf
	s_waitcnt lgkmcnt(0)
	v_add_f32_e32 v16, v16, v17
	s_nop 1
	v_mov_b32_dpp v17, v16 row_half_mirror row_mask:0xf bank_mask:0xf
	s_waitcnt lgkmcnt(0)
	v_add_f32_e32 v16, v16, v17
	s_nop 1
	v_mov_b32_dpp v17, v16 row_mirror row_mask:0xf bank_mask:0xf
	s_waitcnt lgkmcnt(0)
	v_add_f32_e32 v16, v16, v17
	v_mov_b32_e32 v17, v16
	v_mov_b32_e32 v120, v16
	s_nop 1
	v_permlane16_swap_b32_e32 v17, v120
	s_waitcnt lgkmcnt(0)
	v_add_f32_e32 v16, v17, v120
	v_mov_b32_e32 v17, v16
	v_mov_b32_e32 v120, v16
	s_nop 1
	v_permlane32_swap_b32_e32 v17, v120
	s_and_saveexec_b64 s[38:39], vcc
	s_cbranch_execz .LBB0_487
	s_waitcnt lgkmcnt(0)
	v_add_f32_e32 v8, v17, v120
	v_fmamk_f32 v8, v8, 0x3a800000, v204
	v_mul_f32_e32 v9, 0x4b800000, v8
	v_cmp_gt_f32_e64 s[42:43], s33, v8
	s_nop 1
	v_cndmask_b32_e64 v8, v8, v9, s[42:43]
	v_rsq_f32_e32 v16, v8
	v_lshl_add_u64 v[8:9], v[0:1], 2, s[74:75]
	v_mul_f32_e32 v1, 0x45800000, v16
	v_cndmask_b32_e64 v1, v16, v1, s[42:43]
	global_store_dword v[8:9], v1, off
	s_branch .LBB0_487

; DI int otid() { int t = threadIdx.x; asm volatile("" : "+v"(t)); return t; }
; DI void rw_phase(const float* x, bf16_t* hb, const bf16_t* y, const float* gpost, float* rh, float* fout, bool y_unscaled) {
;   const int tid_ = otid(), wid = tid_ >> 6, lane = tid_ & 63;
;   for (int row = blockIdx.x * 8 + wid; row < T_; row += gridDim.x * 8) {
; __global__ void __launch_bounds__(512, 2) mega(Params p) {
;     ...
;         else rw_phase(nullptr, bU, gy, gl + 1024, rh, nullptr, false);
.LBB0_723:
	s_mov_b32 s5, 0
	v_writelane_b32 v255, s5, 29
	s_andn2_b64 vcc, exec, s[26:27]
	s_mov_b64 s[26:27], 0
	v_writelane_b32 v255, s26, 31
	s_nop 1
	v_writelane_b32 v255, s27, 32
	s_cbranch_vccnz .LBB0_730
	s_add_u32 s22, s20, 0x6000000
	s_addc_u32 s23, s21, 0
	s_add_u32 s26, s20, 0xe000000
	v_writelane_b32 v255, s22, 27
	s_addc_u32 s27, s21, 0
	s_mov_b64 s[42:43], -1
	v_writelane_b32 v255, s23, 28
	s_add_u32 s22, s20, 0x1f100000
	s_addc_u32 s23, s21, 0
	v_writelane_b32 v255, s22, 45
	s_cmp_lt_i32 s91, 3
	s_nop 0
	v_writelane_b32 v255, s23, 46
	s_cbranch_scc1 .LBB0_735
	s_cmp_gt_i32 s91, 3
	s_cbranch_scc0 .LBB0_737
	s_cmp_gt_i32 s91, 4
	v_readlane_b32 s24, v255, 7
	s_movk_i32 s46, 0x7fff
	s_cbranch_scc0 .LBB0_738
	s_add_u32 s64, s20, 0x16000000
	s_addc_u32 s65, s21, 0
	s_cmp_lg_u32 s91, 5
	s_mov_b64 s[22:23], -1
	s_mov_b32 s38, 0x8000
	s_cbranch_scc0 .LBB0_740
	s_waitcnt lgkmcnt(0)
	v_mov_b32_e32 v1, v159
	v_readlane_b32 s5, v254, 4
	v_ashrrev_i32_e32 v0, 6, v1
	s_nop 0
	v_add_u32_e32 v0, s5, v0
	v_cmp_gt_i32_e32 vcc, s38, v0
	s_and_saveexec_b64 s[22:23], vcc
	s_cbranch_execz .LBB0_739
	v_and_b32_e32 v1, 63, v1
	v_lshlrev_b32_e32 v148, 4, v1
	v_cmp_lt_i32_e64 s[42:43], v209, v208
	v_lshl_add_u64 v[2:3], s[30:31], 0, v[148:149]
	v_lshl_add_u64 v[4:5], s[64:65], 0, v[148:149]
	v_lshlrev_b32_e32 v148, 5, v1
	v_cmp_eq_u32_e32 vcc, 0, v1
	v_cndmask_b32_e64 v1, v206, v209, s[42:43]
	v_cmp_lt_i32_e64 s[42:43], v210, v208
	v_lshlrev_b32_e32 v10, 2, v1
	v_readlane_b32 s38, v255, 37
	v_cndmask_b32_e64 v1, v206, v210, s[42:43]
	v_cmp_lt_i32_e64 s[42:43], v211, v208
	v_lshlrev_b32_e32 v11, 2, v1
	v_readlane_b32 s39, v255, 38
	v_cndmask_b32_e64 v1, v206, v211, s[42:43]
	v_lshlrev_b32_e32 v12, 2, v1
	v_xor_b32_e32 v1, 8, v206
	v_cmp_lt_i32_e64 s[42:43], v1, v208
	v_lshl_add_u64 v[6:7], s[38:39], 0, v[148:149]
	s_mov_b64 s[38:39], 0x1000
	v_cndmask_b32_e64 v1, v206, v1, s[42:43]
	v_lshlrev_b32_e32 v13, 2, v1
	v_xor_b32_e32 v1, 16, v206
	v_cmp_lt_i32_e64 s[42:43], v1, v208
	v_lshl_add_u64 v[6:7], v[6:7], 0, s[38:39]
	s_mov_b64 s[38:39], 0
	v_cndmask_b32_e64 v1, v206, v1, s[42:43]
	v_cmp_lt_i32_e64 s[42:43], v214, v208
	v_lshlrev_b32_e32 v14, 2, v1
	s_nop 0
	v_cndmask_b32_e64 v1, v206, v214, s[42:43]
	v_lshlrev_b32_e32 v15, 2, v1
	global_load_dwordx4 v[76:79], v[6:7], off offset:16
	global_load_dwordx4 v[80:83], v[6:7], off
	global_load_dwordx4 v[84:87], v[6:7], off offset:2064
	global_load_dwordx4 v[88:91], v[6:7], off offset:2048
	s_branch .LBB0_733

; DI float bflo(unsigned w) { return __uint_as_float(w << 16); }
; DI float bfhi(unsigned w) { return __uint_as_float(w & 0xffff0000u); }
; DI void rw_phase(const float* x, bf16_t* hb, const bf16_t* y, const float* gpost, float* rh, float* fout, bool y_unscaled) {
;     ...
;     if (y) {
;       float yv[16]; float ss = 0.f;
; #pragma unroll
;       for (int c = 0; c < 2; ++c) {
;         const u32x4 w = gld<u32x4>(y + (size_t)row * 1024 + 512 * c + 8 * lane);
;         yv[8 * c + 0] = bflo(w.x); yv[8 * c + 1] = bfhi(w.x); yv[8 * c + 2] = bflo(w.y); yv[8 * c + 3] = bfhi(w.y);
;         yv[8 * c + 4] = bflo(w.z); yv[8 * c + 5] = bfhi(w.z); yv[8 * c + 6] = bflo(w.w); yv[8 * c + 7] = bfhi(w.w);
;       }
; #pragma unroll
;       for (int i = 0; i < 16; ++i) ss += yv[i] * yv[i];
;       ss = wave_sum(ss);
;       float epsn = EPS;
;       if (y_unscaled) { const float r = gld<float>(rh + row), r2 = r * r; epsn = EPS / (r2 * r2); }
;       const float ry = rsqrtf(ss * (1.0f / 1024.0f) + epsn);
; #pragma unroll
;       for (int c = 0; c < 2; ++c) {
;         const f32x4 g0 = gld<f32x4>(gpost + 512 * c + 8 * lane), g1 = gld<f32x4>(gpost + 512 * c + 8 * lane + 4);
; #pragma unroll
;         for (int i = 0; i < 4; ++i) { hv[8 * c + i] += yv[8 * c + i] * ry * g0[i]; hv[8 * c + 4 + i] += yv[8 * c + 4 + i] * ry * g1[i]; }
;       }
;     }
;     if (fout) {
;       float* op = fout + (size_t)row * 1024;
; #pragma unroll
;       for (int c = 0; c < 2; ++c) {
;         gst<f32x4>(op + 512 * c + 8 * lane, (f32x4){hv[8 * c], hv[8 * c + 1], hv[8 * c + 2], hv[8 * c + 3]});
;         gst<f32x4>(op + 512 * c + 8 * lane + 4, (f32x4){hv[8 * c + 4], hv[8 * c + 5], hv[8 * c + 6], hv[8 * c + 7]});
;       }
;     } else {
;       float s2 = 0.f;
; #pragma unroll
;       for (int c = 0; c < 2; ++c) {
;         u32x4 w;
;         w.x = pk(hv[8 * c + 0], hv[8 * c + 1]); w.y = pk(hv[8 * c + 2], hv[8 * c + 3]); w.z = pk(hv[8 * c + 4], hv[8 * c + 5]); w.w = pk(hv[8 * c + 6], hv[8 * c + 7]);
;         gst<u32x4>(hb + (size_t)row * 1024 + 512 * c + 8 * lane, w);
;         s2 += bflo(w.x) * bflo(w.x) + bfhi(w.x) * bfhi(w.x) + bflo(w.y) * bflo(w.y) + bfhi(w.y) * bfhi(w.y) +
;               bflo(w.z) * bflo(w.z) + bfhi(w.z) * bfhi(w.z) + bflo(w.w) * bflo(w.w) + bfhi(w.w) * bfhi(w.w);
;       }
;       s2 = wave_sum(s2);
;       if (lane == 0) gst<float>(rh + row, rsqrtf(s2 * (1.0f / 1024.0f) + EPS));
.LBB0_733:
	v_ashrrev_i32_e32 v1, 31, v0
	v_lshlrev_b64 v[8:9], 11, v[0:1]
	v_lshl_add_u64 v[20:21], v[4:5], 0, v[8:9]
	s_waitcnt lgkmcnt(0)
	global_load_dwordx4 v[16:19], v[20:21], off offset:1024
	s_nop 0
	global_load_dwordx4 v[20:23], v[20:21], off
	v_lshl_add_u64 v[8:9], v[2:3], 0, v[8:9]
	global_load_dwordx4 v[24:27], v[8:9], off offset:1024
	global_load_dwordx4 v[28:31], v[8:9], off
	s_waitcnt vmcnt(0)
	v_lshlrev_b32_e32 v48, 16, v19
	v_lshlrev_b32_e32 v56, 16, v20
	v_and_b32_e32 v57, 0xffff0000, v20
	v_and_b32_e32 v49, 0xffff0000, v19
	v_lshlrev_b32_e32 v50, 16, v18
	v_and_b32_e32 v51, 0xffff0000, v18
	v_lshlrev_b32_e32 v18, 16, v17
	v_and_b32_e32 v19, 0xffff0000, v17
	v_lshlrev_b32_e32 v52, 16, v16
	v_and_b32_e32 v53, 0xffff0000, v16
	v_lshlrev_b32_e32 v16, 16, v23
	v_and_b32_e32 v17, 0xffff0000, v23
	v_lshlrev_b32_e32 v54, 16, v22
	v_and_b32_e32 v55, 0xffff0000, v22
	v_lshlrev_b32_e32 v22, 16, v21
	v_and_b32_e32 v23, 0xffff0000, v21
	v_pk_mul_f32 v[70:71], v[56:57], v[56:57]
	v_pk_mul_f32 v[68:69], v[22:23], v[22:23]
	v_add_f32_e32 v70, v70, v71
	v_add_f32_e32 v68, v68, v70
	v_pk_mul_f32 v[66:67], v[54:55], v[54:55]
	v_add_f32_e32 v68, v69, v68
	v_add_f32_e32 v66, v66, v68
	v_pk_mul_f32 v[64:65], v[16:17], v[16:17]
	v_add_f32_e32 v66, v67, v66
	v_add_f32_e32 v64, v64, v66
	v_pk_mul_f32 v[62:63], v[52:53], v[52:53]
	v_add_f32_e32 v64, v65, v64
	v_add_f32_e32 v62, v62, v64
	v_pk_mul_f32 v[60:61], v[18:19], v[18:19]
	v_add_f32_e32 v62, v63, v62
	v_add_f32_e32 v60, v60, v62
	v_pk_mul_f32 v[58:59], v[50:51], v[50:51]
	v_add_f32_e32 v60, v61, v60
	v_add_f32_e32 v58, v58, v60
	v_pk_mul_f32 v[20:21], v[48:49], v[48:49]
	v_add_f32_e32 v58, v59, v58
	v_add_f32_e32 v20, v20, v58
	v_add_f32_e32 v20, v21, v20
	s_nop 1
	v_mov_b32_dpp v21, v20 quad_perm:[1,0,3,2] row_mask:0xf bank_mask:0xf
	v_and_b32_e32 v59, 0xffff0000, v26
	s_waitcnt lgkmcnt(0)
	v_add_f32_e32 v20, v20, v21
	s_nop 1
	v_mov_b32_dpp v21, v20 quad_perm:[2,3,0,1] row_mask:0xf bank_mask:0xf
	s_waitcnt lgkmcnt(0)
	v_add_f32_e32 v21, v20, v21
	s_nop 1
	v_mov_b32_dpp v58, v21 row_half_mirror row_mask:0xf bank_mask:0xf
	v_lshlrev_b32_e32 v20, 16, v27
	s_waitcnt lgkmcnt(0)
	v_add_f32_e32 v60, v21, v58
	s_nop 1
	v_mov_b32_dpp v61, v60 row_mirror row_mask:0xf bank_mask:0xf
	v_and_b32_e32 v21, 0xffff0000, v27
	v_lshlrev_b32_e32 v58, 16, v26
	v_lshlrev_b32_e32 v26, 16, v25
	v_and_b32_e32 v27, 0xffff0000, v25
	s_waitcnt lgkmcnt(0)
	v_add_f32_e32 v62, v60, v61
	v_mov_b32_e32 v63, v62
	v_mov_b32_e32 v120, v62
	s_nop 1
	v_permlane16_swap_b32_e32 v63, v120
	v_lshlrev_b32_e32 v60, 16, v24
	v_and_b32_e32 v61, 0xffff0000, v24
	v_lshlrev_b32_e32 v24, 16, v31
	v_and_b32_e32 v25, 0xffff0000, v31
	s_waitcnt lgkmcnt(0)
	v_add_f32_e32 v64, v63, v120
	v_mov_b32_e32 v65, v64
	v_mov_b32_e32 v120, v64
	s_nop 1
	v_permlane32_swap_b32_e32 v65, v120
	v_lshlrev_b32_e32 v62, 16, v30
	v_and_b32_e32 v63, 0xffff0000, v30
	v_lshlrev_b32_e32 v30, 16, v29
	s_waitcnt lgkmcnt(0)
	v_add_f32_e32 v31, v65, v120
	v_fmamk_f32 v31, v31, 0x3a800000, v204
	v_mul_f32_e32 v64, 0x4b800000, v31
	v_cmp_gt_f32_e64 s[42:43], s33, v31
	v_and_b32_e32 v65, 0xffff0000, v28
	s_nop 0
	v_cndmask_b32_e64 v31, v31, v64, s[42:43]
	v_rsq_f32_e32 v66, v31
	v_lshlrev_b32_e32 v64, 16, v28
	v_and_b32_e32 v31, 0xffff0000, v29
	v_mul_f32_e32 v28, 0x45800000, v66
	v_cndmask_b32_e64 v28, v66, v28, s[42:43]
	v_pk_mul_f32 v[56:57], v[28:29], v[56:57] op_sel_hi:[0,1]
	v_pk_mul_f32 v[22:23], v[28:29], v[22:23] op_sel_hi:[0,1]
	v_pk_mul_f32 v[16:17], v[28:29], v[16:17] op_sel_hi:[0,1]
	v_pk_mul_f32 v[52:53], v[28:29], v[52:53] op_sel_hi:[0,1]
	v_pk_mul_f32 v[54:55], v[28:29], v[54:55] op_sel_hi:[0,1]
	v_pk_mul_f32 v[18:19], v[28:29], v[18:19] op_sel_hi:[0,1]
	v_pk_fma_f32 v[36:37], v[80:81], v[56:57], v[64:65]
	v_pk_fma_f32 v[22:23], v[82:83], v[22:23], v[30:31]
	v_pk_fma_f32 v[16:17], v[78:79], v[16:17], v[24:25]
	v_pk_fma_f32 v[24:25], v[88:89], v[52:53], v[60:61]
	v_pk_mul_f32 v[50:51], v[28:29], v[50:51] op_sel_hi:[0,1]
	v_pk_mul_f32 v[28:29], v[28:29], v[48:49] op_sel_hi:[0,1]
	v_pk_fma_f32 v[32:33], v[76:77], v[54:55], v[62:63]
	v_pk_fma_f32 v[26:27], v[90:91], v[18:19], v[26:27]
	v_cvt_pk_bf16_f32 v18, v36, v37
	v_cvt_pk_bf16_f32 v19, v22, v23
	v_cvt_pk_bf16_f32 v22, v24, v25
	v_pk_fma_f32 v[28:29], v[86:87], v[28:29], v[20:21]
	v_cvt_pk_bf16_f32 v20, v32, v33
	v_cvt_pk_bf16_f32 v21, v16, v17
	v_and_b32_e32 v17, 0xffff0000, v18
	v_and_b32_e32 v33, 0xffff0000, v22
	v_cvt_pk_bf16_f32 v23, v26, v27
	v_lshlrev_b32_e32 v16, 16, v18
	v_lshlrev_b32_e32 v32, 16, v22
	v_mul_f32_e32 v17, v17, v17
	v_mul_f32_e32 v33, v33, v33
	v_pk_fma_f32 v[30:31], v[84:85], v[50:51], v[58:59]
	v_lshlrev_b32_e32 v26, 16, v19
	v_lshlrev_b32_e32 v34, 16, v23
	v_fmac_f32_e32 v17, v16, v16
	v_fmac_f32_e32 v33, v32, v32
	v_cvt_pk_bf16_f32 v24, v30, v31
	v_and_b32_e32 v27, 0xffff0000, v19
	v_and_b32_e32 v35, 0xffff0000, v23
	v_fmac_f32_e32 v17, v26, v26
	v_fmac_f32_e32 v33, v34, v34
	v_cvt_pk_bf16_f32 v25, v28, v29
	v_lshlrev_b32_e32 v28, 16, v20
	v_lshlrev_b32_e32 v36, 16, v24
	v_fmac_f32_e32 v17, v27, v27
	v_fmac_f32_e32 v33, v35, v35
	v_and_b32_e32 v29, 0xffff0000, v20
	v_and_b32_e32 v37, 0xffff0000, v24
	v_fmac_f32_e32 v17, v28, v28
	v_fmac_f32_e32 v33, v36, v36
	v_lshlrev_b32_e32 v30, 16, v21
	v_lshlrev_b32_e32 v38, 16, v25
	v_fmac_f32_e32 v17, v29, v29
	v_fmac_f32_e32 v33, v37, v37
	v_and_b32_e32 v31, 0xffff0000, v21
	v_and_b32_e32 v39, 0xffff0000, v25
	v_fmac_f32_e32 v17, v30, v30
	v_fmac_f32_e32 v33, v38, v38
	v_fmac_f32_e32 v17, v31, v31
	v_fmac_f32_e32 v33, v39, v39
	v_add_f32_e32 v16, v17, v33
	s_nop 1
	v_mov_b32_dpp v17, v16 quad_perm:[1,0,3,2] row_mask:0xf bank_mask:0xf
	global_store_dwordx4 v[8:9], v[18:21], off
	global_store_dwordx4 v[8:9], v[22:25], off offset:1024
	s_waitcnt lgkmcnt(0)
	v_add_f32_e32 v16, v16, v17
	s_nop 1
	v_mov_b32_dpp v17, v16 quad_perm:[2,3,0,1] row_mask:0xf bank_mask:0xf
	s_waitcnt lgkmcnt(0)
	v_add_f32_e32 v16, v16, v17
	s_nop 1
	v_mov_b32_dpp v17, v16 row_half_mirror row_mask:0xf bank_mask:0xf
	s_waitcnt lgkmcnt(0)
	v_add_f32_e32 v16, v16, v17
	s_nop 1
	v_mov_b32_dpp v17, v16 row_mirror row_mask:0xf bank_mask:0xf
	s_waitcnt lgkmcnt(0)
	v_add_f32_e32 v16, v16, v17
	v_mov_b32_e32 v17, v16
	v_mov_b32_e32 v120, v16
	s_nop 1
	v_permlane16_swap_b32_e32 v17, v120
	s_waitcnt lgkmcnt(0)
	v_add_f32_e32 v16, v17, v120
	v_mov_b32_e32 v17, v16
	v_mov_b32_e32 v120, v16
	s_nop 1
	v_permlane32_swap_b32_e32 v17, v120
	s_and_saveexec_b64 s[44:45], vcc
	s_cbranch_execz .LBB0_732
	s_waitcnt lgkmcnt(0)
	v_add_f32_e32 v8, v17, v120
	v_fmamk_f32 v8, v8, 0x3a800000, v204
	v_mul_f32_e32 v9, 0x4b800000, v8
	v_cmp_gt_f32_e64 s[42:43], s33, v8
	s_nop 1
	v_cndmask_b32_e64 v8, v8, v9, s[42:43]
	v_rsq_f32_e32 v16, v8
	v_lshl_add_u64 v[8:9], v[0:1], 2, s[74:75]
	v_mul_f32_e32 v1, 0x45800000, v16
	v_cndmask_b32_e64 v1, v16, v1, s[42:43]
	global_store_dword v[8:9], v1, off
	s_branch .LBB0_732

; DI int otid() { int t = threadIdx.x; asm volatile("" : "+v"(t)); return t; }
; DI void rw_phase(const float* x, bf16_t* hb, const bf16_t* y, const float* gpost, float* rh, float* fout, bool y_unscaled) {
;   const int tid_ = otid(), wid = tid_ >> 6, lane = tid_ & 63;
;   for (int row = blockIdx.x * 8 + wid; row < T_; row += gridDim.x * 8) {
; __global__ void __launch_bounds__(512, 2) mega(Params p) {
;     ...
;         else rw_phase(nullptr, bU, bA, gl + 1024, rh, nullptr, false);
.LBB0_895:
	v_readlane_b32 s22, v254, 0
	v_readlane_b32 s23, v254, 1
	s_mov_b32 s5, 32
	s_load_dwordx2 s[22:23], s[22:23], s5
	s_waitcnt lgkmcnt(0)
	s_cmp_lt_i32 s91, 2
	s_mov_b64 s[42:43], -1
	s_cbranch_scc1 .LBB0_904
	s_cmp_gt_i32 s91, 2
	s_cbranch_scc0 .LBB0_905
	s_cmp_gt_i32 s91, 3
	v_readlane_b32 s24, v255, 7
	s_mov_b32 s38, 0x8000
	s_movk_i32 s46, 0x7fff
	s_cbranch_scc0 .LBB0_906
	s_cmp_lg_u32 s91, 4
	s_mov_b64 s[26:27], -1
	s_cbranch_scc0 .LBB0_909
	s_waitcnt lgkmcnt(0)
	v_mov_b32_e32 v1, v159
	v_readlane_b32 s5, v254, 4
	v_ashrrev_i32_e32 v0, 6, v1
	s_nop 0
	v_add_u32_e32 v0, s5, v0
	v_cmp_gt_i32_e32 vcc, s38, v0
	s_and_saveexec_b64 s[26:27], vcc
	s_cbranch_execz .LBB0_908
	v_and_b32_e32 v1, 63, v1
	v_lshlrev_b32_e32 v148, 4, v1
	v_cmp_lt_i32_e64 s[42:43], v209, v208
	v_lshl_add_u64 v[2:3], s[30:31], 0, v[148:149]
	v_lshl_add_u64 v[4:5], s[34:35], 0, v[148:149]
	v_lshlrev_b32_e32 v148, 5, v1
	v_cmp_eq_u32_e32 vcc, 0, v1
	v_cndmask_b32_e64 v1, v206, v209, s[42:43]
	v_cmp_lt_i32_e64 s[42:43], v210, v208
	v_lshlrev_b32_e32 v10, 2, v1
	v_readlane_b32 s38, v255, 37
	v_cndmask_b32_e64 v1, v206, v210, s[42:43]
	v_cmp_lt_i32_e64 s[42:43], v211, v208
	v_lshlrev_b32_e32 v11, 2, v1
	v_readlane_b32 s39, v255, 38
	v_cndmask_b32_e64 v1, v206, v211, s[42:43]
	v_lshlrev_b32_e32 v12, 2, v1
	v_xor_b32_e32 v1, 8, v206
	v_cmp_lt_i32_e64 s[42:43], v1, v208
	v_lshl_add_u64 v[6:7], s[38:39], 0, v[148:149]
	s_mov_b64 s[38:39], 0x1000
	v_cndmask_b32_e64 v1, v206, v1, s[42:43]
	v_lshlrev_b32_e32 v13, 2, v1
	v_xor_b32_e32 v1, 16, v206
	v_cmp_lt_i32_e64 s[42:43], v1, v208
	v_lshl_add_u64 v[6:7], v[6:7], 0, s[38:39]
	s_mov_b64 s[38:39], 0
	v_cndmask_b32_e64 v1, v206, v1, s[42:43]
	v_cmp_lt_i32_e64 s[42:43], v214, v208
	v_lshlrev_b32_e32 v14, 2, v1
	s_nop 0
	v_cndmask_b32_e64 v1, v206, v214, s[42:43]
	v_lshlrev_b32_e32 v15, 2, v1
	global_load_dwordx4 v[76:79], v[6:7], off offset:16
	global_load_dwordx4 v[80:83], v[6:7], off
	global_load_dwordx4 v[84:87], v[6:7], off offset:2064
	global_load_dwordx4 v[88:91], v[6:7], off offset:2048
	s_branch .LBB0_902
